# plus U (FF1 output, FF2 A operand) stored k-tile-major per 128-token panel: FF1 phase hand-written (128x128 tile, MFMA stream pipelined across the k-tile barrier) with tiled stores, FF2 loader offsets
# baseline (speedup 1.0000x reference)
.LBB0_1282:
	s_or_b64 exec, exec, s[6:7]
	s_barrier
	s_mov_b32 s22, s2
	s_cmpk_gt_i32 s22, 0x27ff
	s_cbranch_scc1 .Lhwff1a_done
	v_and_b32_e32 v148, 63, v193
	v_lshrrev_b32_e32 v149, 6, v193
	s_nop 1
	v_readfirstlane_b32 s6, v149
	s_nop 3
	s_lshr_b32 s7, s6, 1
	s_and_b32 s30, s6, 1
	s_lshl_b32 s24, s6, 10
	s_add_u32 s25, s24, 0x4000
	v_lshrrev_b32_e32 v150, 3, v148
	s_lshl_b32 s34, s6, 3
	v_add_u32_e32 v150, s34, v150
	v_bfe_u32 v152, v150, 1, 3
	v_and_b32_e32 v151, 7, v148
	v_xor_b32_e32 v151, v151, v152
	v_lshlrev_b32_e32 v151, 4, v151
	v_lshl_add_u32 v128, v150, 11, v151
	v_add_u32_e32 v129, 0x10000, v128
	v_add_u32_e32 v130, 0x20000, v128
	v_add_u32_e32 v131, 0x30000, v128
	v_lshl_add_u32 v132, v150, 11, v151
	v_add_u32_e32 v133, 0x10000, v132
	v_add_u32_e32 v134, 0x20000, v132
	v_add_u32_e32 v135, 0x30000, v132
	v_and_b32_e32 v150, 15, v148
	v_lshrrev_b32_e32 v151, 4, v148
	v_lshrrev_b32_e32 v152, 1, v150
	v_xor_b32_e32 v152, v151, v152
	v_lshlrev_b32_e32 v152, 4, v152
	v_lshl_add_u32 v152, v150, 7, v152
	s_lshl_b32 s34, s7, 13
	v_add_u32_e32 v136, s34, v152
	s_lshl_b32 s34, s30, 13
	s_add_u32 s34, s34, 0x4000
	v_add_u32_e32 v137, s34, v152
	v_xor_b32_e32 v138, 64, v136
	v_xor_b32_e32 v139, 64, v137
	v_and_b32_e32 v152, 1, v151
	v_lshlrev_b32_e32 v152, 4, v152
	v_lshrrev_b32_e32 v153, 1, v151
	v_lshl_add_u32 v152, v153, 3, v152
	v_lshlrev_b32_e32 v152, 1, v152
	s_lshl_b32 s34, s30, 14
	v_add_u32_e32 v152, s34, v152
	s_lshl_b32 s34, s7, 6
	v_add_u32_e32 v153, s34, v150
	v_lshl_add_u32 v144, v153, 7, v152
	v_mov_b32_e32 v145, 0
	s_mov_b32 s28, 0x800
	s_mov_b32 s29, 0
	s_brev_b32 s10, -2
	s_mov_b32 s11, 0x20000
	s_mov_b32 s14, s10
	s_mov_b32 s15, s11
	s_mov_b32 s23, s22
	s_mov_b32 s17, 0
	s_mov_b32 s16, 0
	s_mov_b32 s20, 0
	s_mov_b32 s19, 0
	s_mov_b32 s18, 0
	s_and_b32 s37, s23, 7
	s_lshr_b32 s38, s23, 3
	s_and_b32 s39, s38, 63
	s_lshr_b32 s44, s38, 6
	s_lshl_b32 s44, s44, 3
	s_add_u32 s44, s44, s37
	s_lshr_b32 s35, s44, 2
	s_lshl_b32 s35, s35, 3
	s_and_b32 s45, s39, 7
	s_add_u32 s35, s35, s45
	s_and_b32 s36, s44, 3
	s_lshl_b32 s36, s36, 3
	s_lshr_b32 s45, s39, 3
	s_add_u32 s36, s36, s45
	s_lshl_b32 s45, s35, 18
	s_add_u32 s45, s45, 0x3cb8000
	s_add_u32 s8, s40, s45
	s_addc_u32 s9, s41, 0
	s_and_b32 s9, s9, 0xffff
	s_lshl_b32 s45, s36, 18
	s_add_u32 s45, s45, 0xe20000
	s_add_u32 s12, s40, s45
	s_addc_u32 s13, s41, 0
	s_and_b32 s13, s13, 0xffff
	s_add_u32 s30, s24, s19
	s_add_u32 s31, s25, s19
	s_add_u32 m0, s30, 0x0
	s_nop 0
	buffer_load_dwordx4 v128, s[8:11], s20 offen lds
	s_add_u32 m0, s30, 0x1000
	s_nop 0
	buffer_load_dwordx4 v129, s[8:11], s20 offen lds
	s_add_u32 m0, s30, 0x2000
	s_nop 0
	buffer_load_dwordx4 v130, s[8:11], s20 offen lds
	s_add_u32 m0, s30, 0x3000
	s_nop 0
	buffer_load_dwordx4 v131, s[8:11], s20 offen lds
	s_add_u32 m0, s31, 0x0
	s_nop 0
	buffer_load_dwordx4 v132, s[12:15], s20 offen lds
	s_add_u32 m0, s31, 0x1000
	s_nop 0
	buffer_load_dwordx4 v133, s[12:15], s20 offen lds
	s_add_u32 m0, s31, 0x2000
	s_nop 0
	buffer_load_dwordx4 v134, s[12:15], s20 offen lds
	s_add_u32 m0, s31, 0x3000
	s_nop 0
	buffer_load_dwordx4 v135, s[12:15], s20 offen lds
	s_add_u32 s20, s20, 128
	s_add_u32 s16, s16, 1
	s_xor_b32 s19, s19, 0x8000
	s_add_u32 s30, s24, s19
	s_add_u32 s31, s25, s19
	s_add_u32 m0, s30, 0x0
	s_nop 0
	buffer_load_dwordx4 v128, s[8:11], s20 offen lds
	s_add_u32 m0, s30, 0x1000
	s_nop 0
	buffer_load_dwordx4 v129, s[8:11], s20 offen lds
	s_add_u32 m0, s30, 0x2000
	s_nop 0
	buffer_load_dwordx4 v130, s[8:11], s20 offen lds
	s_add_u32 m0, s30, 0x3000
	s_nop 0
	buffer_load_dwordx4 v131, s[8:11], s20 offen lds
	s_add_u32 m0, s31, 0x0
	s_nop 0
	buffer_load_dwordx4 v132, s[12:15], s20 offen lds
	s_add_u32 m0, s31, 0x1000
	s_nop 0
	buffer_load_dwordx4 v133, s[12:15], s20 offen lds
	s_add_u32 m0, s31, 0x2000
	s_nop 0
	buffer_load_dwordx4 v134, s[12:15], s20 offen lds
	s_add_u32 m0, s31, 0x3000
	s_nop 0
	buffer_load_dwordx4 v135, s[12:15], s20 offen lds
	s_add_u32 s20, s20, 128
	s_add_u32 s16, s16, 1
	s_xor_b32 s19, s19, 0x8000
	s_and_b32 s37, s22, 7
	s_lshr_b32 s38, s22, 3
	s_and_b32 s39, s38, 63
	s_lshr_b32 s44, s38, 6
	s_lshl_b32 s44, s44, 3
	s_add_u32 s44, s44, s37
	s_lshr_b32 s35, s44, 2
	s_lshl_b32 s35, s35, 3
	s_and_b32 s45, s39, 7
	s_add_u32 s35, s35, s45
	s_and_b32 s36, s44, 3
	s_lshl_b32 s36, s36, 3
	s_lshr_b32 s45, s39, 3
	s_add_u32 s36, s36, s45
	s_lshl_b32 s45, s35, 20
	s_lshl_b32 s46, s36, 15
	s_add_u32 s45, s45, s46
	s_add_u32 s45, s45, 0x8cb8000
	s_add_u32 s26, s40, s45
	s_addc_u32 s27, s41, 0
	s_waitcnt vmcnt(0)
	s_barrier
	v_add_u32_e32 v140, s18, v136
	v_add_u32_e32 v141, s18, v137
	ds_read_b128 v[64:67], v140 offset:0
	ds_read_b128 v[68:71], v140 offset:2048
	ds_read_b128 v[72:75], v140 offset:4096
	ds_read_b128 v[76:79], v140 offset:6144
	ds_read_b128 v[80:83], v141 offset:0
	ds_read_b128 v[84:87], v141 offset:2048
	ds_read_b128 v[88:91], v141 offset:4096
	ds_read_b128 v[92:95], v141 offset:6144
	v_add_u32_e32 v142, s18, v138
	v_add_u32_e32 v143, s18, v139
	ds_read_b128 v[96:99], v142 offset:0
	ds_read_b128 v[100:103], v142 offset:2048
	ds_read_b128 v[104:107], v142 offset:4096
	ds_read_b128 v[108:111], v142 offset:6144
	ds_read_b128 v[112:115], v143 offset:0
	ds_read_b128 v[116:119], v143 offset:2048
	ds_read_b128 v[120:123], v143 offset:4096
	ds_read_b128 v[124:127], v143 offset:6144
	s_xor_b32 s18, s18, 0x8000
.Lhwff1a_tile:
	v_mov_b32_e32 v0, 0
	v_mov_b32_e32 v1, 0
	v_mov_b32_e32 v2, 0
	v_mov_b32_e32 v3, 0
	v_mov_b32_e32 v4, 0
	v_mov_b32_e32 v5, 0
	v_mov_b32_e32 v6, 0
	v_mov_b32_e32 v7, 0
	v_mov_b32_e32 v8, 0
	v_mov_b32_e32 v9, 0
	v_mov_b32_e32 v10, 0
	v_mov_b32_e32 v11, 0
	v_mov_b32_e32 v12, 0
	v_mov_b32_e32 v13, 0
	v_mov_b32_e32 v14, 0
	v_mov_b32_e32 v15, 0
	v_mov_b32_e32 v16, 0
	v_mov_b32_e32 v17, 0
	v_mov_b32_e32 v18, 0
	v_mov_b32_e32 v19, 0
	v_mov_b32_e32 v20, 0
	v_mov_b32_e32 v21, 0
	v_mov_b32_e32 v22, 0
	v_mov_b32_e32 v23, 0
	v_mov_b32_e32 v24, 0
	v_mov_b32_e32 v25, 0
	v_mov_b32_e32 v26, 0
	v_mov_b32_e32 v27, 0
	v_mov_b32_e32 v28, 0
	v_mov_b32_e32 v29, 0
	v_mov_b32_e32 v30, 0
	v_mov_b32_e32 v31, 0
	v_mov_b32_e32 v32, 0
	v_mov_b32_e32 v33, 0
	v_mov_b32_e32 v34, 0
	v_mov_b32_e32 v35, 0
	v_mov_b32_e32 v36, 0
	v_mov_b32_e32 v37, 0
	v_mov_b32_e32 v38, 0
	v_mov_b32_e32 v39, 0
	v_mov_b32_e32 v40, 0
	v_mov_b32_e32 v41, 0
	v_mov_b32_e32 v42, 0
	v_mov_b32_e32 v43, 0
	v_mov_b32_e32 v44, 0
	v_mov_b32_e32 v45, 0
	v_mov_b32_e32 v46, 0
	v_mov_b32_e32 v47, 0
	v_mov_b32_e32 v48, 0
	v_mov_b32_e32 v49, 0
	v_mov_b32_e32 v50, 0
	v_mov_b32_e32 v51, 0
	v_mov_b32_e32 v52, 0
	v_mov_b32_e32 v53, 0
	v_mov_b32_e32 v54, 0
	v_mov_b32_e32 v55, 0
	v_mov_b32_e32 v56, 0
	v_mov_b32_e32 v57, 0
	v_mov_b32_e32 v58, 0
	v_mov_b32_e32 v59, 0
	v_mov_b32_e32 v60, 0
	v_mov_b32_e32 v61, 0
	v_mov_b32_e32 v62, 0
	v_mov_b32_e32 v63, 0
	s_mov_b32 s21, 0
.Lhwff1a_loop:
	s_waitcnt lgkmcnt(11)
	v_mfma_f32_16x16x32_bf16 v[0:3], v[80:83], v[64:67], v[0:3]
	v_mfma_f32_16x16x32_bf16 v[16:19], v[80:83], v[68:71], v[16:19]
	v_mfma_f32_16x16x32_bf16 v[32:35], v[80:83], v[72:75], v[32:35]
	v_mfma_f32_16x16x32_bf16 v[48:51], v[80:83], v[76:79], v[48:51]
	s_waitcnt lgkmcnt(10)
	v_mfma_f32_16x16x32_bf16 v[4:7], v[84:87], v[64:67], v[4:7]
	v_mfma_f32_16x16x32_bf16 v[20:23], v[84:87], v[68:71], v[20:23]
	v_mfma_f32_16x16x32_bf16 v[36:39], v[84:87], v[72:75], v[36:39]
	v_mfma_f32_16x16x32_bf16 v[52:55], v[84:87], v[76:79], v[52:55]
	s_waitcnt lgkmcnt(9)
	v_mfma_f32_16x16x32_bf16 v[8:11], v[88:91], v[64:67], v[8:11]
	v_mfma_f32_16x16x32_bf16 v[24:27], v[88:91], v[68:71], v[24:27]
	v_mfma_f32_16x16x32_bf16 v[40:43], v[88:91], v[72:75], v[40:43]
	v_mfma_f32_16x16x32_bf16 v[56:59], v[88:91], v[76:79], v[56:59]
	s_waitcnt lgkmcnt(8)
	v_mfma_f32_16x16x32_bf16 v[12:15], v[92:95], v[64:67], v[12:15]
	v_mfma_f32_16x16x32_bf16 v[28:31], v[92:95], v[68:71], v[28:31]
	v_mfma_f32_16x16x32_bf16 v[44:47], v[92:95], v[72:75], v[44:47]
	v_mfma_f32_16x16x32_bf16 v[60:63], v[92:95], v[76:79], v[60:63]
	s_waitcnt lgkmcnt(0)
	s_cmp_eq_u32 s21, 0
	s_cbranch_scc1 .Lhwff1a_wst
	s_waitcnt vmcnt(0)
	s_branch .Lhwff1a_go
.Lhwff1a_wst:
	s_waitcnt vmcnt(8)
.Lhwff1a_go:
	s_barrier
	v_add_u32_e32 v140, s18, v136
	v_add_u32_e32 v141, s18, v137
	ds_read_b128 v[64:67], v140 offset:0
	ds_read_b128 v[68:71], v140 offset:2048
	ds_read_b128 v[72:75], v140 offset:4096
	ds_read_b128 v[76:79], v140 offset:6144
	ds_read_b128 v[80:83], v141 offset:0
	ds_read_b128 v[84:87], v141 offset:2048
	ds_read_b128 v[88:91], v141 offset:4096
	ds_read_b128 v[92:95], v141 offset:6144
	s_cmp_eq_u32 s17, 1
	s_cbranch_scc1 .Lhwff1a_nodma
	s_add_u32 s30, s24, s19
	s_add_u32 s31, s25, s19
	s_add_u32 m0, s30, 0x0
	v_mfma_f32_16x16x32_bf16 v[0:3], v[112:115], v[96:99], v[0:3]
	v_mfma_f32_16x16x32_bf16 v[16:19], v[112:115], v[100:103], v[16:19]
	buffer_load_dwordx4 v128, s[8:11], s20 offen lds
	s_add_u32 m0, s30, 0x1000
	v_mfma_f32_16x16x32_bf16 v[32:35], v[112:115], v[104:107], v[32:35]
	v_mfma_f32_16x16x32_bf16 v[48:51], v[112:115], v[108:111], v[48:51]
	buffer_load_dwordx4 v129, s[8:11], s20 offen lds
	s_add_u32 m0, s30, 0x2000
	v_mfma_f32_16x16x32_bf16 v[4:7], v[116:119], v[96:99], v[4:7]
	v_mfma_f32_16x16x32_bf16 v[20:23], v[116:119], v[100:103], v[20:23]
	buffer_load_dwordx4 v130, s[8:11], s20 offen lds
	s_add_u32 m0, s30, 0x3000
	v_mfma_f32_16x16x32_bf16 v[36:39], v[116:119], v[104:107], v[36:39]
	v_mfma_f32_16x16x32_bf16 v[52:55], v[116:119], v[108:111], v[52:55]
	buffer_load_dwordx4 v131, s[8:11], s20 offen lds
	s_add_u32 m0, s31, 0x0
	v_mfma_f32_16x16x32_bf16 v[8:11], v[120:123], v[96:99], v[8:11]
	v_mfma_f32_16x16x32_bf16 v[24:27], v[120:123], v[100:103], v[24:27]
	buffer_load_dwordx4 v132, s[12:15], s20 offen lds
	s_add_u32 m0, s31, 0x1000
	v_mfma_f32_16x16x32_bf16 v[40:43], v[120:123], v[104:107], v[40:43]
	v_mfma_f32_16x16x32_bf16 v[56:59], v[120:123], v[108:111], v[56:59]
	buffer_load_dwordx4 v133, s[12:15], s20 offen lds
	s_add_u32 m0, s31, 0x2000
	v_mfma_f32_16x16x32_bf16 v[12:15], v[124:127], v[96:99], v[12:15]
	v_mfma_f32_16x16x32_bf16 v[28:31], v[124:127], v[100:103], v[28:31]
	buffer_load_dwordx4 v134, s[12:15], s20 offen lds
	s_add_u32 m0, s31, 0x3000
	v_mfma_f32_16x16x32_bf16 v[44:47], v[124:127], v[104:107], v[44:47]
	v_mfma_f32_16x16x32_bf16 v[60:63], v[124:127], v[108:111], v[60:63]
	buffer_load_dwordx4 v135, s[12:15], s20 offen lds
	s_add_u32 s20, s20, 128
	s_add_u32 s16, s16, 1
	s_xor_b32 s19, s19, 0x8000
	s_cmp_lt_u32 s16, 16
	s_cbranch_scc1 .Lhwff1a_next
	s_mov_b32 s16, 0
	s_mov_b32 s20, 0
	s_add_u32 s23, s23, s3
	s_cmpk_lt_i32 s23, 0x2800
	s_cbranch_scc1 .Lhwff1a_nextbases
	s_mov_b32 s17, 1
	s_branch .Lhwff1a_next
.Lhwff1a_nextbases:
	s_and_b32 s37, s23, 7
	s_lshr_b32 s38, s23, 3
	s_and_b32 s39, s38, 63
	s_lshr_b32 s44, s38, 6
	s_lshl_b32 s44, s44, 3
	s_add_u32 s44, s44, s37
	s_lshr_b32 s35, s44, 2
	s_lshl_b32 s35, s35, 3
	s_and_b32 s45, s39, 7
	s_add_u32 s35, s35, s45
	s_and_b32 s36, s44, 3
	s_lshl_b32 s36, s36, 3
	s_lshr_b32 s45, s39, 3
	s_add_u32 s36, s36, s45
	s_lshl_b32 s45, s35, 18
	s_add_u32 s45, s45, 0x3cb8000
	s_add_u32 s8, s40, s45
	s_addc_u32 s9, s41, 0
	s_and_b32 s9, s9, 0xffff
	s_lshl_b32 s45, s36, 18
	s_add_u32 s45, s45, 0xe20000
	s_add_u32 s12, s40, s45
	s_addc_u32 s13, s41, 0
	s_and_b32 s13, s13, 0xffff
	s_branch .Lhwff1a_next
.Lhwff1a_nodma:
	v_mfma_f32_16x16x32_bf16 v[0:3], v[112:115], v[96:99], v[0:3]
	v_mfma_f32_16x16x32_bf16 v[16:19], v[112:115], v[100:103], v[16:19]
	v_mfma_f32_16x16x32_bf16 v[32:35], v[112:115], v[104:107], v[32:35]
	v_mfma_f32_16x16x32_bf16 v[48:51], v[112:115], v[108:111], v[48:51]
	v_mfma_f32_16x16x32_bf16 v[4:7], v[116:119], v[96:99], v[4:7]
	v_mfma_f32_16x16x32_bf16 v[20:23], v[116:119], v[100:103], v[20:23]
	v_mfma_f32_16x16x32_bf16 v[36:39], v[116:119], v[104:107], v[36:39]
	v_mfma_f32_16x16x32_bf16 v[52:55], v[116:119], v[108:111], v[52:55]
	v_mfma_f32_16x16x32_bf16 v[8:11], v[120:123], v[96:99], v[8:11]
	v_mfma_f32_16x16x32_bf16 v[24:27], v[120:123], v[100:103], v[24:27]
	v_mfma_f32_16x16x32_bf16 v[40:43], v[120:123], v[104:107], v[40:43]
	v_mfma_f32_16x16x32_bf16 v[56:59], v[120:123], v[108:111], v[56:59]
	v_mfma_f32_16x16x32_bf16 v[12:15], v[124:127], v[96:99], v[12:15]
	v_mfma_f32_16x16x32_bf16 v[28:31], v[124:127], v[100:103], v[28:31]
	v_mfma_f32_16x16x32_bf16 v[44:47], v[124:127], v[104:107], v[44:47]
	v_mfma_f32_16x16x32_bf16 v[60:63], v[124:127], v[108:111], v[60:63]
.Lhwff1a_next:
	v_add_u32_e32 v142, s18, v138
	v_add_u32_e32 v143, s18, v139
	ds_read_b128 v[96:99], v142 offset:0
	ds_read_b128 v[100:103], v142 offset:2048
	ds_read_b128 v[104:107], v142 offset:4096
	ds_read_b128 v[108:111], v142 offset:6144
	ds_read_b128 v[112:115], v143 offset:0
	ds_read_b128 v[116:119], v143 offset:2048
	ds_read_b128 v[120:123], v143 offset:4096
	ds_read_b128 v[124:127], v143 offset:6144
	s_xor_b32 s18, s18, 0x8000
	s_add_u32 s21, s21, 1
	s_cmp_lt_u32 s21, 16
	s_cbranch_scc1 .Lhwff1a_loop
	s_nop 7
	s_nop 1
	v_lshl_add_u64 v[146:147], v[144:145], 0, s[26:27]
	v_max_f32_e32 v0, 0, v0
	v_max_f32_e32 v1, 0, v1
	v_max_f32_e32 v2, 0, v2
	v_max_f32_e32 v3, 0, v3
	v_max_f32_e32 v4, 0, v4
	v_max_f32_e32 v5, 0, v5
	v_max_f32_e32 v6, 0, v6
	v_max_f32_e32 v7, 0, v7
	v_mul_f32_e32 v0, v0, v0
	v_mul_f32_e32 v1, v1, v1
	v_mul_f32_e32 v2, v2, v2
	v_mul_f32_e32 v3, v3, v3
	v_mul_f32_e32 v4, v4, v4
	v_mul_f32_e32 v5, v5, v5
	v_mul_f32_e32 v6, v6, v6
	v_mul_f32_e32 v7, v7, v7
	v_cvt_pk_bf16_f32 v0, v0, v1
	v_cvt_pk_bf16_f32 v1, v2, v3
	v_cvt_pk_bf16_f32 v2, v4, v5
	v_cvt_pk_bf16_f32 v3, v6, v7
	s_nop 1
	v_permlane16_swap_b32_e32 v0, v2
	v_permlane16_swap_b32_e32 v1, v3
	global_store_dwordx4 v[146:147], v[0:3], off nt
	v_max_f32_e32 v8, 0, v8
	v_max_f32_e32 v9, 0, v9
	v_max_f32_e32 v10, 0, v10
	v_max_f32_e32 v11, 0, v11
	v_max_f32_e32 v12, 0, v12
	v_max_f32_e32 v13, 0, v13
	v_max_f32_e32 v14, 0, v14
	v_max_f32_e32 v15, 0, v15
	v_mul_f32_e32 v8, v8, v8
	v_mul_f32_e32 v9, v9, v9
	v_mul_f32_e32 v10, v10, v10
	v_mul_f32_e32 v11, v11, v11
	v_mul_f32_e32 v12, v12, v12
	v_mul_f32_e32 v13, v13, v13
	v_mul_f32_e32 v14, v14, v14
	v_mul_f32_e32 v15, v15, v15
	v_cvt_pk_bf16_f32 v8, v8, v9
	v_cvt_pk_bf16_f32 v9, v10, v11
	v_cvt_pk_bf16_f32 v10, v12, v13
	v_cvt_pk_bf16_f32 v11, v14, v15
	s_nop 1
	v_permlane16_swap_b32_e32 v8, v10
	v_permlane16_swap_b32_e32 v9, v11
	global_store_dwordx4 v[146:147], v[8:11], off offset:64 nt
	v_lshl_add_u64 v[146:147], v[146:147], 0, s[28:29]
	v_max_f32_e32 v16, 0, v16
	v_max_f32_e32 v17, 0, v17
	v_max_f32_e32 v18, 0, v18
	v_max_f32_e32 v19, 0, v19
	v_max_f32_e32 v20, 0, v20
	v_max_f32_e32 v21, 0, v21
	v_max_f32_e32 v22, 0, v22
	v_max_f32_e32 v23, 0, v23
	v_mul_f32_e32 v16, v16, v16
	v_mul_f32_e32 v17, v17, v17
	v_mul_f32_e32 v18, v18, v18
	v_mul_f32_e32 v19, v19, v19
	v_mul_f32_e32 v20, v20, v20
	v_mul_f32_e32 v21, v21, v21
	v_mul_f32_e32 v22, v22, v22
	v_mul_f32_e32 v23, v23, v23
	v_cvt_pk_bf16_f32 v16, v16, v17
	v_cvt_pk_bf16_f32 v17, v18, v19
	v_cvt_pk_bf16_f32 v18, v20, v21
	v_cvt_pk_bf16_f32 v19, v22, v23
	s_nop 1
	v_permlane16_swap_b32_e32 v16, v18
	v_permlane16_swap_b32_e32 v17, v19
	global_store_dwordx4 v[146:147], v[16:19], off nt
	v_max_f32_e32 v24, 0, v24
	v_max_f32_e32 v25, 0, v25
	v_max_f32_e32 v26, 0, v26
	v_max_f32_e32 v27, 0, v27
	v_max_f32_e32 v28, 0, v28
	v_max_f32_e32 v29, 0, v29
	v_max_f32_e32 v30, 0, v30
	v_max_f32_e32 v31, 0, v31
	v_mul_f32_e32 v24, v24, v24
	v_mul_f32_e32 v25, v25, v25
	v_mul_f32_e32 v26, v26, v26
	v_mul_f32_e32 v27, v27, v27
	v_mul_f32_e32 v28, v28, v28
	v_mul_f32_e32 v29, v29, v29
	v_mul_f32_e32 v30, v30, v30
	v_mul_f32_e32 v31, v31, v31
	v_cvt_pk_bf16_f32 v24, v24, v25
	v_cvt_pk_bf16_f32 v25, v26, v27
	v_cvt_pk_bf16_f32 v26, v28, v29
	v_cvt_pk_bf16_f32 v27, v30, v31
	s_nop 1
	v_permlane16_swap_b32_e32 v24, v26
	v_permlane16_swap_b32_e32 v25, v27
	global_store_dwordx4 v[146:147], v[24:27], off offset:64 nt
	v_lshl_add_u64 v[146:147], v[146:147], 0, s[28:29]
	v_max_f32_e32 v32, 0, v32
	v_max_f32_e32 v33, 0, v33
	v_max_f32_e32 v34, 0, v34
	v_max_f32_e32 v35, 0, v35
	v_max_f32_e32 v36, 0, v36
	v_max_f32_e32 v37, 0, v37
	v_max_f32_e32 v38, 0, v38
	v_max_f32_e32 v39, 0, v39
	v_mul_f32_e32 v32, v32, v32
	v_mul_f32_e32 v33, v33, v33
	v_mul_f32_e32 v34, v34, v34
	v_mul_f32_e32 v35, v35, v35
	v_mul_f32_e32 v36, v36, v36
	v_mul_f32_e32 v37, v37, v37
	v_mul_f32_e32 v38, v38, v38
	v_mul_f32_e32 v39, v39, v39
	v_cvt_pk_bf16_f32 v32, v32, v33
	v_cvt_pk_bf16_f32 v33, v34, v35
	v_cvt_pk_bf16_f32 v34, v36, v37
	v_cvt_pk_bf16_f32 v35, v38, v39
	s_nop 1
	v_permlane16_swap_b32_e32 v32, v34
	v_permlane16_swap_b32_e32 v33, v35
	global_store_dwordx4 v[146:147], v[32:35], off nt
	v_max_f32_e32 v40, 0, v40
	v_max_f32_e32 v41, 0, v41
	v_max_f32_e32 v42, 0, v42
	v_max_f32_e32 v43, 0, v43
	v_max_f32_e32 v44, 0, v44
	v_max_f32_e32 v45, 0, v45
	v_max_f32_e32 v46, 0, v46
	v_max_f32_e32 v47, 0, v47
	v_mul_f32_e32 v40, v40, v40
	v_mul_f32_e32 v41, v41, v41
	v_mul_f32_e32 v42, v42, v42
	v_mul_f32_e32 v43, v43, v43
	v_mul_f32_e32 v44, v44, v44
	v_mul_f32_e32 v45, v45, v45
	v_mul_f32_e32 v46, v46, v46
	v_mul_f32_e32 v47, v47, v47
	v_cvt_pk_bf16_f32 v40, v40, v41
	v_cvt_pk_bf16_f32 v41, v42, v43
	v_cvt_pk_bf16_f32 v42, v44, v45
	v_cvt_pk_bf16_f32 v43, v46, v47
	s_nop 1
	v_permlane16_swap_b32_e32 v40, v42
	v_permlane16_swap_b32_e32 v41, v43
	global_store_dwordx4 v[146:147], v[40:43], off offset:64 nt
	v_lshl_add_u64 v[146:147], v[146:147], 0, s[28:29]
	v_max_f32_e32 v48, 0, v48
	v_max_f32_e32 v49, 0, v49
	v_max_f32_e32 v50, 0, v50
	v_max_f32_e32 v51, 0, v51
	v_max_f32_e32 v52, 0, v52
	v_max_f32_e32 v53, 0, v53
	v_max_f32_e32 v54, 0, v54
	v_max_f32_e32 v55, 0, v55
	v_mul_f32_e32 v48, v48, v48
	v_mul_f32_e32 v49, v49, v49
	v_mul_f32_e32 v50, v50, v50
	v_mul_f32_e32 v51, v51, v51
	v_mul_f32_e32 v52, v52, v52
	v_mul_f32_e32 v53, v53, v53
	v_mul_f32_e32 v54, v54, v54
	v_mul_f32_e32 v55, v55, v55
	v_cvt_pk_bf16_f32 v48, v48, v49
	v_cvt_pk_bf16_f32 v49, v50, v51
	v_cvt_pk_bf16_f32 v50, v52, v53
	v_cvt_pk_bf16_f32 v51, v54, v55
	s_nop 1
	v_permlane16_swap_b32_e32 v48, v50
	v_permlane16_swap_b32_e32 v49, v51
	global_store_dwordx4 v[146:147], v[48:51], off nt
	v_max_f32_e32 v56, 0, v56
	v_max_f32_e32 v57, 0, v57
	v_max_f32_e32 v58, 0, v58
	v_max_f32_e32 v59, 0, v59
	v_max_f32_e32 v60, 0, v60
	v_max_f32_e32 v61, 0, v61
	v_max_f32_e32 v62, 0, v62
	v_max_f32_e32 v63, 0, v63
	v_mul_f32_e32 v56, v56, v56
	v_mul_f32_e32 v57, v57, v57
	v_mul_f32_e32 v58, v58, v58
	v_mul_f32_e32 v59, v59, v59
	v_mul_f32_e32 v60, v60, v60
	v_mul_f32_e32 v61, v61, v61
	v_mul_f32_e32 v62, v62, v62
	v_mul_f32_e32 v63, v63, v63
	v_cvt_pk_bf16_f32 v56, v56, v57
	v_cvt_pk_bf16_f32 v57, v58, v59
	v_cvt_pk_bf16_f32 v58, v60, v61
	v_cvt_pk_bf16_f32 v59, v62, v63
	s_nop 1
	v_permlane16_swap_b32_e32 v56, v58
	v_permlane16_swap_b32_e32 v57, v59
	global_store_dwordx4 v[146:147], v[56:59], off offset:64 nt
	s_add_u32 s22, s22, s3
	s_cmpk_lt_i32 s22, 0x2800
	s_cbranch_scc0 .Lhwff1a_done
	s_and_b32 s37, s22, 7
	s_lshr_b32 s38, s22, 3
	s_and_b32 s39, s38, 63
	s_lshr_b32 s44, s38, 6
	s_lshl_b32 s44, s44, 3
	s_add_u32 s44, s44, s37
	s_lshr_b32 s35, s44, 2
	s_lshl_b32 s35, s35, 3
	s_and_b32 s45, s39, 7
	s_add_u32 s35, s35, s45
	s_and_b32 s36, s44, 3
	s_lshl_b32 s36, s36, 3
	s_lshr_b32 s45, s39, 3
	s_add_u32 s36, s36, s45
	s_lshl_b32 s45, s35, 20
	s_lshl_b32 s46, s36, 15
	s_add_u32 s45, s45, s46
	s_add_u32 s45, s45, 0x8cb8000
	s_add_u32 s26, s40, s45
	s_addc_u32 s27, s41, 0
	s_branch .Lhwff1a_tile
.Lhwff1a_done:
	s_waitcnt lgkmcnt(0)
.LBB0_1297:
	s_waitcnt vmcnt(0)
	s_waitcnt vmcnt(8)
	s_barrier
	s_mov_b64 s[6:7], exec
	v_readlane_b32 s8, v244, 0
	v_readlane_b32 s9, v244, 1
	s_and_b64 s[8:9], s[6:7], s[8:9]
	s_mov_b64 exec, s[8:9]
	s_cbranch_execz .LBB0_1350
	v_cmp_eq_u32_e32 vcc, 0, v192
	s_waitcnt vmcnt(0) expcnt(0) lgkmcnt(0)
	s_and_saveexec_b64 s[8:9], vcc
	s_cbranch_execz .LBB0_1313
	s_add_u32 s10, s40, 0x1f718200
	s_addc_u32 s11, s41, 0
	s_add_u32 s12, s40, 0x1f718400
	s_addc_u32 s13, s41, 0
	s_add_u32 s14, s40, 0x1f718500
	s_addc_u32 s15, s41, 0
	s_add_u32 s16, s40, 0x1f718600
	s_addc_u32 s17, s41, 0
	s_add_u32 s18, s40, 0x1f718700
	s_addc_u32 s19, s41, 0
	s_add_u32 s20, s40, 0x1f718800
	s_addc_u32 s21, s41, 0
	s_add_u32 s22, s40, 0x1f718900
	s_addc_u32 s23, s41, 0
	s_add_u32 s24, s40, 0x1f718a00
	s_addc_u32 s25, s41, 0
	s_add_u32 s26, s40, 0x1f718b00
	s_addc_u32 s27, s41, 0
	s_add_u32 s28, s40, 0x1f718c00
	s_addc_u32 s29, s41, 0
	s_add_u32 s34, s40, 0x1f718d00
	s_addc_u32 s35, s41, 0
	s_add_u32 s36, s40, 0x1f718e00
	s_addc_u32 s37, s41, 0
	s_add_u32 s38, s40, 0x1f718f00
	s_addc_u32 s39, s41, 0
	s_add_u32 s44, s40, 0x1f719000
	s_addc_u32 s45, s41, 0
	s_add_u32 s46, s40, 0x1f719100
	s_addc_u32 s47, s41, 0
	s_add_u32 s48, s40, 0x1f719200
	s_addc_u32 s49, s41, 0
	s_add_u32 s50, s40, 0x1f719300
	s_addc_u32 s51, s41, 0
	s_mov_b32 s58, 1
	v_mov_b32_e32 v16, 0
	s_branch .LBB0_1301

.LBB0_1355:
	s_ashr_i32 s17, s12, 6
	s_and_b32 s6, s12, 7
	s_and_b32 s17, s17, 0x1ffffff8
	s_or_b32 s6, s17, s6
	s_lshl_b32 s6, s6, 3
	s_bfe_u32 s17, s12, 0x30003
	s_or_b32 s6, s6, s17
	s_xor_b64 s[22:23], s[22:23], -1
	s_bfe_u32 s37, s12, 0x30006
	s_sub_i32 s26, 0x13f, s6
	s_ashr_i32 s12, s16, 31
	s_waitcnt lgkmcnt(0)
	s_add_u32 s16, s10, s16
	s_addc_u32 s12, s11, s12
	s_add_u32 s45, s16, 0x8cb8000
	s_addc_u32 s46, s12, 0
	s_ashr_i32 s12, s13, 31
	s_add_u32 s13, s10, s13
	s_addc_u32 s12, s11, s12
	s_add_u32 s47, s13, 0x1620000
	v_mov_b32 v0, 0
	s_addc_u32 s48, s12, 0
	s_ashr_i32 s27, s26, 31
	v_add_u32_e32 v0, v0, v193
	s_lshl_b64 s[12:13], s[26:27], 20
	v_lshrrev_b32_e32 v1, 4, v0
	s_add_u32 s12, s45, s12
	v_xor_b32_e32 v2, v1, v0
	v_lshlrev_b32_e32 v3, 9, v0
	s_addc_u32 s13, s46, s13
	s_lshl_b32 s16, s37, 20
	v_lshlrev_b32_e32 v2, 3, v2
	v_and_b32_e32 v3, 0x7ffff000, v3
	s_add_u32 s16, s47, s16
	v_and_or_b32 v2, v2, 56, v3
	s_addc_u32 s17, s48, 0
	v_lshlrev_b32_e32 v67, 1, v2
	v_lshlrev_b32_e32 v68, 4, v0
	v_readfirstlane_b32 s27, v0
	s_and_b32 s13, s13, 0xffff
	s_and_b32 s17, s17, 0xffff
	v_add_u32_e32 v66, 0x40000, v67
	v_add_u32_e32 v65, 0x80000, v67
	v_add_u32_e32 v64, 0xc0000, v67
	v_lshrrev_b32_e32 v245, 13, v67
	v_and_b32_e32 v246, 0x7f, v67
	v_lshl_or_b32 v245, v245, 7, v246
	v_add_u32_e32 v246, 0x1000, v245
	v_add_u32_e32 v247, 0x2000, v245
	v_add_u32_e32 v248, 0x3000, v245
	s_mov_b64 s[18:19], -1
	s_and_b64 vcc, exec, s[22:23]
	v_add_u32_e32 v69, 0x4000, v68
	v_add_u32_e32 v2, 0x1000, v68
	v_add_u32_e32 v3, 0x2000, v68
	v_add_u32_e32 v4, 0x3000, v68
	s_cbranch_vccz .LBB0_1357
	v_readfirstlane_b32 s18, v68
	s_mov_b32 m0, s18
	v_readfirstlane_b32 s22, v69
	v_add_u32_e32 v70, 0x1000, v68
	buffer_load_dwordx4 v245, s[12:15], 0 offen lds
	s_mov_b32 s18, s14
	s_mov_b32 s19, s15
	s_mov_b32 m0, s22
	v_readfirstlane_b32 s22, v70
	v_add_u32_e32 v5, 0x5000, v68
	buffer_load_dwordx4 v67, s[16:19], 0 offen lds
	s_mov_b32 m0, s22
	v_readfirstlane_b32 s22, v5
	v_add_u32_e32 v71, 0x2000, v68
	buffer_load_dwordx4 v246, s[12:15], 0 offen lds
	s_mov_b32 m0, s22
	v_readfirstlane_b32 s22, v71
	v_add_u32_e32 v5, 0x6000, v68
	buffer_load_dwordx4 v66, s[16:19], 0 offen lds
	s_mov_b32 m0, s22
	v_readfirstlane_b32 s22, v5
	v_add_u32_e32 v72, 0x3000, v68
	buffer_load_dwordx4 v247, s[12:15], 0 offen lds
	s_mov_b32 m0, s22
	v_readfirstlane_b32 s22, v72
	v_add_u32_e32 v5, 0x7000, v68
	buffer_load_dwordx4 v65, s[16:19], 0 offen lds
	s_mov_b32 m0, s22
	v_readfirstlane_b32 s22, v5
	buffer_load_dwordx4 v248, s[12:15], 0 offen lds
	s_mov_b32 m0, s22
	s_nop 0
	buffer_load_dwordx4 v64, s[16:19], 0 offen lds
	s_mov_b64 s[18:19], 0

.LBB0_1359:
	v_bfe_u32 v3, v0, 1, 3
	v_and_b32_e32 v2, 3, v1
	v_bitop3_b32 v1, v1, v3, 3 bitop3:0x6c
	s_lshl_b32 s18, s27, 6
	v_lshlrev_b32_e32 v75, 4, v1
	v_bitop3_b32 v1, v2, v3, 4 bitop3:0x36
	s_and_b32 s49, s18, 0xffffe000
	v_lshlrev_b32_e32 v0, 7, v0
	s_lshl_b32 s18, s27, 7
	v_mov_b32_e32 v40, 0
	s_mov_b64 s[22:23], s[28:29]
	v_lshlrev_b32_e32 v74, 4, v1
	v_and_b32_e32 v73, 0x780, v0
	s_and_b32 s27, s18, 0x2000
	s_movk_i32 s50, 0x80
	s_movk_i32 s98, 0x4000
	s_mov_b32 s51, 0
	s_mov_b32 s18, s14
	s_mov_b32 s19, s15
	v_mov_b32_e32 v41, v40
	v_mov_b32_e32 v42, v40
	v_mov_b32_e32 v43, v40
	v_mov_b32_e32 v0, v40
	v_mov_b32_e32 v1, v40
	v_mov_b32_e32 v2, v40
	v_mov_b32_e32 v3, v40
	v_mov_b32_e32 v4, v40
	v_mov_b32_e32 v5, v40
	v_mov_b32_e32 v6, v40
	v_mov_b32_e32 v7, v40
	v_mov_b32_e32 v8, v40
	v_mov_b32_e32 v9, v40
	v_mov_b32_e32 v10, v40
	v_mov_b32_e32 v11, v40
	v_mov_b32_e32 v12, v40
	v_mov_b32_e32 v13, v40
	s_waitcnt vmcnt(0)
	v_mov_b32_e32 v14, v40
	v_mov_b32_e32 v15, v40
	v_mov_b32_e32 v16, v40
	v_mov_b32_e32 v17, v40
	v_mov_b32_e32 v18, v40
	v_mov_b32_e32 v19, v40
	v_mov_b32_e32 v20, v40
	v_mov_b32_e32 v21, v40
	v_mov_b32_e32 v22, v40
	v_mov_b32_e32 v23, v40
	v_mov_b32_e32 v24, v40
	v_mov_b32_e32 v25, v40
	v_mov_b32_e32 v26, v40
	v_mov_b32_e32 v27, v40
	v_mov_b32_e32 v28, v40
	v_mov_b32_e32 v29, v40
	v_mov_b32_e32 v30, v40
	v_mov_b32_e32 v31, v40
	v_mov_b32_e32 v32, v40
	v_mov_b32_e32 v33, v40
	v_mov_b32_e32 v34, v40
	v_mov_b32_e32 v35, v40
	v_mov_b32_e32 v36, v40
	v_mov_b32_e32 v37, v40
	v_mov_b32_e32 v38, v40
	v_mov_b32_e32 v39, v40
	v_mov_b32_e32 v44, v40
	v_mov_b32_e32 v45, v40
	v_mov_b32_e32 v46, v40
	v_mov_b32_e32 v47, v40
	v_mov_b32_e32 v48, v40
	v_mov_b32_e32 v49, v40
	v_mov_b32_e32 v50, v40
	v_mov_b32_e32 v51, v40
	v_mov_b32_e32 v52, v40
	v_mov_b32_e32 v53, v40
	v_mov_b32_e32 v54, v40
	v_mov_b32_e32 v55, v40
	v_mov_b32_e32 v56, v40
	v_mov_b32_e32 v57, v40
	v_mov_b32_e32 v58, v40
	v_mov_b32_e32 v59, v40
	v_mov_b32_e32 v60, v40
	v_mov_b32_e32 v61, v40
	v_mov_b32_e32 v62, v40
	v_mov_b32_e32 v63, v40
.LBB0_1360:
	s_add_i32 s30, s51, 0x8000
	s_and_b32 s52, s30, 0x8000
	v_add_u32_e32 v76, s52, v68
	s_waitcnt vmcnt(0)
	s_nop 0
	v_readfirstlane_b32 s31, v76
	v_add_u32_e32 v76, 0x4000, v76
	s_mov_b32 m0, s31
	v_readfirstlane_b32 s31, v76
	v_add_u32_e32 v76, s52, v70
	s_barrier
	buffer_load_dwordx4 v245, s[12:15], s98 offen lds
	s_mov_b32 m0, s31
	v_readfirstlane_b32 s31, v76
	v_add_u32_e32 v76, 0x4000, v76
	buffer_load_dwordx4 v67, s[16:19], s50 offen lds
	s_mov_b32 m0, s31
	v_readfirstlane_b32 s31, v76
	v_add_u32_e32 v76, s52, v71
	buffer_load_dwordx4 v246, s[12:15], s98 offen lds
	s_mov_b32 m0, s31
	v_readfirstlane_b32 s31, v76
	v_add_u32_e32 v76, 0x4000, v76
	buffer_load_dwordx4 v66, s[16:19], s50 offen lds
	s_mov_b32 m0, s31
	v_readfirstlane_b32 s31, v76
	v_add_u32_e32 v76, s52, v72
	buffer_load_dwordx4 v247, s[12:15], s98 offen lds
	s_mov_b32 m0, s31
	v_readfirstlane_b32 s31, v76
	v_add_u32_e32 v76, 0x4000, v76
	buffer_load_dwordx4 v65, s[16:19], s50 offen lds
	s_mov_b32 m0, s31
	v_readfirstlane_b32 s31, v76
	buffer_load_dwordx4 v248, s[12:15], s98 offen lds
	s_mov_b32 m0, s31
	s_and_b32 s31, s51, 0x8000
	buffer_load_dwordx4 v64, s[16:19], s50 offen lds
	v_or_b32_e32 v80, s31, v75
	v_add3_u32 v83, v80, s49, v73
	v_add3_u32 v80, v80, s27, v73
	ds_read_b128 v[76:79], v83
	ds_read_b128 v[84:87], v83 offset:2048
	ds_read_b128 v[88:91], v83 offset:4096
	ds_read_b128 v[92:95], v83 offset:6144
	ds_read_b128 v[96:99], v80 offset:16384
	ds_read_b128 v[100:103], v80 offset:18432
	ds_read_b128 v[104:107], v80 offset:20480
	ds_read_b128 v[108:111], v80 offset:22528
	v_or_b32_e32 v80, s31, v74
	v_add3_u32 v83, v80, s49, v73
	v_add3_u32 v80, v80, s27, v73
	ds_read_b128 v[112:115], v83
	ds_read_b128 v[116:119], v83 offset:2048
	ds_read_b128 v[120:123], v83 offset:4096
	ds_read_b128 v[124:127], v83 offset:6144
	ds_read_b128 v[128:131], v80 offset:16384
	ds_read_b128 v[132:135], v80 offset:18432
	ds_read_b128 v[136:139], v80 offset:20480
	ds_read_b128 v[140:143], v80 offset:22528
	s_waitcnt lgkmcnt(11)
	v_mfma_f32_16x16x32_bf16 v[60:63], v[96:99], v[76:79], v[60:63]
	s_waitcnt lgkmcnt(10)
	v_mfma_f32_16x16x32_bf16 v[56:59], v[100:103], v[76:79], v[56:59]
	s_waitcnt lgkmcnt(9)
	v_mfma_f32_16x16x32_bf16 v[52:55], v[104:107], v[76:79], v[52:55]
	s_waitcnt lgkmcnt(8)
	v_mfma_f32_16x16x32_bf16 v[48:51], v[108:111], v[76:79], v[48:51]
	v_mfma_f32_16x16x32_bf16 v[44:47], v[96:99], v[84:87], v[44:47]
	v_mfma_f32_16x16x32_bf16 v[36:39], v[100:103], v[84:87], v[36:39]
	v_mfma_f32_16x16x32_bf16 v[32:35], v[104:107], v[84:87], v[32:35]
	v_mfma_f32_16x16x32_bf16 v[28:31], v[108:111], v[84:87], v[28:31]
	v_mfma_f32_16x16x32_bf16 v[24:27], v[96:99], v[88:91], v[24:27]
	v_mfma_f32_16x16x32_bf16 v[20:23], v[100:103], v[88:91], v[20:23]
	v_mfma_f32_16x16x32_bf16 v[16:19], v[104:107], v[88:91], v[16:19]
	v_mfma_f32_16x16x32_bf16 v[12:15], v[108:111], v[88:91], v[12:15]
	v_mfma_f32_16x16x32_bf16 v[8:11], v[96:99], v[92:95], v[8:11]
	v_mfma_f32_16x16x32_bf16 v[4:7], v[100:103], v[92:95], v[4:7]
	v_mfma_f32_16x16x32_bf16 v[0:3], v[104:107], v[92:95], v[0:3]
	v_mfma_f32_16x16x32_bf16 v[40:43], v[108:111], v[92:95], v[40:43]
	s_waitcnt lgkmcnt(3)
	v_mfma_f32_16x16x32_bf16 v[60:63], v[128:131], v[112:115], v[60:63]
	s_addk_i32 s50, 0x80
	s_addk_i32 s98, 0x4000
	s_cmpk_eq_i32 s50, 0x2000
	s_mov_b32 s51, s30
	s_waitcnt lgkmcnt(2)
	v_mfma_f32_16x16x32_bf16 v[56:59], v[132:135], v[112:115], v[56:59]
	s_waitcnt lgkmcnt(1)
	v_mfma_f32_16x16x32_bf16 v[52:55], v[136:139], v[112:115], v[52:55]
	s_waitcnt lgkmcnt(0)
	v_mfma_f32_16x16x32_bf16 v[48:51], v[140:143], v[112:115], v[48:51]
	v_mfma_f32_16x16x32_bf16 v[44:47], v[128:131], v[116:119], v[44:47]
	v_mfma_f32_16x16x32_bf16 v[36:39], v[132:135], v[116:119], v[36:39]
	v_mfma_f32_16x16x32_bf16 v[32:35], v[136:139], v[116:119], v[32:35]
	v_mfma_f32_16x16x32_bf16 v[28:31], v[140:143], v[116:119], v[28:31]
	v_mfma_f32_16x16x32_bf16 v[24:27], v[128:131], v[120:123], v[24:27]
	v_mfma_f32_16x16x32_bf16 v[20:23], v[132:135], v[120:123], v[20:23]
	v_mfma_f32_16x16x32_bf16 v[16:19], v[136:139], v[120:123], v[16:19]
	v_mfma_f32_16x16x32_bf16 v[12:15], v[140:143], v[120:123], v[12:15]
	v_mfma_f32_16x16x32_bf16 v[8:11], v[128:131], v[124:127], v[8:11]
	v_mfma_f32_16x16x32_bf16 v[4:7], v[132:135], v[124:127], v[4:7]
	v_mfma_f32_16x16x32_bf16 v[0:3], v[136:139], v[124:127], v[0:3]
	v_mfma_f32_16x16x32_bf16 v[40:43], v[140:143], v[124:127], v[40:43]
	s_cbranch_scc0 .LBB0_1360
	s_waitcnt vmcnt(0)
	s_andn2_b64 vcc, exec, s[28:29]
	s_waitcnt vmcnt(0)
	s_barrier
	s_cbranch_vccnz .LBB0_1363
	s_lshl_b64 s[12:13], s[34:35], 1
	s_add_u32 s12, s45, s12
	s_addc_u32 s13, s46, s13
	s_lshl_b32 s16, s36, 1
	s_add_u32 s16, s47, s16
	v_readfirstlane_b32 s28, v68
	s_addc_u32 s17, s48, 0
	s_and_b32 s13, s13, 0xffff
	s_mov_b32 m0, s28
	v_readfirstlane_b32 s28, v69
	v_add_u32_e32 v78, 0x4000, v70
	s_and_b32 s17, s17, 0xffff
	s_mov_b32 s18, s14
	s_mov_b32 s19, s15
	buffer_load_dwordx4 v245, s[12:15], 0 offen lds
	s_mov_b32 m0, s28
	v_readfirstlane_b32 s28, v70
	buffer_load_dwordx4 v67, s[16:19], 0 offen lds
	s_mov_b32 m0, s28
	v_readfirstlane_b32 s28, v78
	v_add_u32_e32 v77, 0x4000, v71
	buffer_load_dwordx4 v246, s[12:15], 0 offen lds
	s_mov_b32 m0, s28
	v_readfirstlane_b32 s28, v71
	buffer_load_dwordx4 v66, s[16:19], 0 offen lds
	s_mov_b32 m0, s28
	v_readfirstlane_b32 s28, v77
	buffer_load_dwordx4 v247, s[12:15], 0 offen lds
	s_mov_b32 m0, s28
	v_readfirstlane_b32 s28, v72
	v_add_u32_e32 v76, 0x4000, v72
	buffer_load_dwordx4 v65, s[16:19], 0 offen lds
	s_mov_b32 m0, s28
	s_nop 0
	buffer_load_dwordx4 v248, s[12:15], 0 offen lds
	v_readfirstlane_b32 s12, v76
	s_mov_b32 m0, s12
	s_nop 0
	buffer_load_dwordx4 v64, s[16:19], 0 offen lds

.LBB0_2428:
	s_or_b64 exec, exec, s[6:7]
	s_barrier
	s_mov_b32 s22, s2
	s_cmpk_gt_i32 s22, 0x27ff
	s_cbranch_scc1 .Lhwff1b_done
	v_and_b32_e32 v148, 63, v193
	v_lshrrev_b32_e32 v149, 6, v193
	s_nop 1
	v_readfirstlane_b32 s6, v149
	s_nop 3
	s_lshr_b32 s7, s6, 1
	s_and_b32 s30, s6, 1
	s_lshl_b32 s24, s6, 10
	s_add_u32 s25, s24, 0x4000
	v_lshrrev_b32_e32 v150, 3, v148
	s_lshl_b32 s34, s6, 3
	v_add_u32_e32 v150, s34, v150
	v_bfe_u32 v152, v150, 1, 3
	v_and_b32_e32 v151, 7, v148
	v_xor_b32_e32 v151, v151, v152
	v_lshlrev_b32_e32 v151, 4, v151
	v_lshl_add_u32 v128, v150, 11, v151
	v_add_u32_e32 v129, 0x10000, v128
	v_add_u32_e32 v130, 0x20000, v128
	v_add_u32_e32 v131, 0x30000, v128
	v_lshl_add_u32 v132, v150, 11, v151
	v_add_u32_e32 v133, 0x10000, v132
	v_add_u32_e32 v134, 0x20000, v132
	v_add_u32_e32 v135, 0x30000, v132
	v_and_b32_e32 v150, 15, v148
	v_lshrrev_b32_e32 v151, 4, v148
	v_lshrrev_b32_e32 v152, 1, v150
	v_xor_b32_e32 v152, v151, v152
	v_lshlrev_b32_e32 v152, 4, v152
	v_lshl_add_u32 v152, v150, 7, v152
	s_lshl_b32 s34, s7, 13
	v_add_u32_e32 v136, s34, v152
	s_lshl_b32 s34, s30, 13
	s_add_u32 s34, s34, 0x4000
	v_add_u32_e32 v137, s34, v152
	v_xor_b32_e32 v138, 64, v136
	v_xor_b32_e32 v139, 64, v137
	v_and_b32_e32 v152, 1, v151
	v_lshlrev_b32_e32 v152, 4, v152
	v_lshrrev_b32_e32 v153, 1, v151
	v_lshl_add_u32 v152, v153, 3, v152
	v_lshlrev_b32_e32 v152, 1, v152
	s_lshl_b32 s34, s30, 14
	v_add_u32_e32 v152, s34, v152
	s_lshl_b32 s34, s7, 6
	v_add_u32_e32 v153, s34, v150
	v_lshl_add_u32 v144, v153, 7, v152
	v_mov_b32_e32 v145, 0
	s_mov_b32 s28, 0x800
	s_mov_b32 s29, 0
	s_brev_b32 s10, -2
	s_mov_b32 s11, 0x20000
	s_mov_b32 s14, s10
	s_mov_b32 s15, s11
	s_mov_b32 s23, s22
	s_mov_b32 s17, 0
	s_mov_b32 s16, 0
	s_mov_b32 s20, 0
	s_mov_b32 s19, 0
	s_mov_b32 s18, 0
	s_and_b32 s37, s23, 7
	s_lshr_b32 s38, s23, 3
	s_and_b32 s39, s38, 63
	s_lshr_b32 s44, s38, 6
	s_lshl_b32 s44, s44, 3
	s_add_u32 s44, s44, s37
	s_lshr_b32 s35, s44, 2
	s_lshl_b32 s35, s35, 3
	s_and_b32 s45, s39, 7
	s_add_u32 s35, s35, s45
	s_and_b32 s36, s44, 3
	s_lshl_b32 s36, s36, 3
	s_lshr_b32 s45, s39, 3
	s_add_u32 s36, s36, s45
	s_lshl_b32 s45, s35, 18
	s_add_u32 s45, s45, 0x3cb8000
	s_add_u32 s8, s40, s45
	s_addc_u32 s9, s41, 0
	s_and_b32 s9, s9, 0xffff
	s_lshl_b32 s45, s36, 18
	s_add_u32 s45, s45, 0x2c40000
	s_add_u32 s12, s40, s45
	s_addc_u32 s13, s41, 0
	s_and_b32 s13, s13, 0xffff
	s_add_u32 s30, s24, s19
	s_add_u32 s31, s25, s19
	s_add_u32 m0, s30, 0x0
	s_nop 0
	buffer_load_dwordx4 v128, s[8:11], s20 offen lds
	s_add_u32 m0, s30, 0x1000
	s_nop 0
	buffer_load_dwordx4 v129, s[8:11], s20 offen lds
	s_add_u32 m0, s30, 0x2000
	s_nop 0
	buffer_load_dwordx4 v130, s[8:11], s20 offen lds
	s_add_u32 m0, s30, 0x3000
	s_nop 0
	buffer_load_dwordx4 v131, s[8:11], s20 offen lds
	s_add_u32 m0, s31, 0x0
	s_nop 0
	buffer_load_dwordx4 v132, s[12:15], s20 offen lds
	s_add_u32 m0, s31, 0x1000
	s_nop 0
	buffer_load_dwordx4 v133, s[12:15], s20 offen lds
	s_add_u32 m0, s31, 0x2000
	s_nop 0
	buffer_load_dwordx4 v134, s[12:15], s20 offen lds
	s_add_u32 m0, s31, 0x3000
	s_nop 0
	buffer_load_dwordx4 v135, s[12:15], s20 offen lds
	s_add_u32 s20, s20, 128
	s_add_u32 s16, s16, 1
	s_xor_b32 s19, s19, 0x8000
	s_add_u32 s30, s24, s19
	s_add_u32 s31, s25, s19
	s_add_u32 m0, s30, 0x0
	s_nop 0
	buffer_load_dwordx4 v128, s[8:11], s20 offen lds
	s_add_u32 m0, s30, 0x1000
	s_nop 0
	buffer_load_dwordx4 v129, s[8:11], s20 offen lds
	s_add_u32 m0, s30, 0x2000
	s_nop 0
	buffer_load_dwordx4 v130, s[8:11], s20 offen lds
	s_add_u32 m0, s30, 0x3000
	s_nop 0
	buffer_load_dwordx4 v131, s[8:11], s20 offen lds
	s_add_u32 m0, s31, 0x0
	s_nop 0
	buffer_load_dwordx4 v132, s[12:15], s20 offen lds
	s_add_u32 m0, s31, 0x1000
	s_nop 0
	buffer_load_dwordx4 v133, s[12:15], s20 offen lds
	s_add_u32 m0, s31, 0x2000
	s_nop 0
	buffer_load_dwordx4 v134, s[12:15], s20 offen lds
	s_add_u32 m0, s31, 0x3000
	s_nop 0
	buffer_load_dwordx4 v135, s[12:15], s20 offen lds
	s_add_u32 s20, s20, 128
	s_add_u32 s16, s16, 1
	s_xor_b32 s19, s19, 0x8000
	s_and_b32 s37, s22, 7
	s_lshr_b32 s38, s22, 3
	s_and_b32 s39, s38, 63
	s_lshr_b32 s44, s38, 6
	s_lshl_b32 s44, s44, 3
	s_add_u32 s44, s44, s37
	s_lshr_b32 s35, s44, 2
	s_lshl_b32 s35, s35, 3
	s_and_b32 s45, s39, 7
	s_add_u32 s35, s35, s45
	s_and_b32 s36, s44, 3
	s_lshl_b32 s36, s36, 3
	s_lshr_b32 s45, s39, 3
	s_add_u32 s36, s36, s45
	s_lshl_b32 s45, s35, 20
	s_lshl_b32 s46, s36, 15
	s_add_u32 s45, s45, s46
	s_add_u32 s45, s45, 0x8cb8000
	s_add_u32 s26, s40, s45
	s_addc_u32 s27, s41, 0
	s_waitcnt vmcnt(0)
	s_barrier
	v_add_u32_e32 v140, s18, v136
	v_add_u32_e32 v141, s18, v137
	ds_read_b128 v[64:67], v140 offset:0
	ds_read_b128 v[68:71], v140 offset:2048
	ds_read_b128 v[72:75], v140 offset:4096
	ds_read_b128 v[76:79], v140 offset:6144
	ds_read_b128 v[80:83], v141 offset:0
	ds_read_b128 v[84:87], v141 offset:2048
	ds_read_b128 v[88:91], v141 offset:4096
	ds_read_b128 v[92:95], v141 offset:6144
	v_add_u32_e32 v142, s18, v138
	v_add_u32_e32 v143, s18, v139
	ds_read_b128 v[96:99], v142 offset:0
	ds_read_b128 v[100:103], v142 offset:2048
	ds_read_b128 v[104:107], v142 offset:4096
	ds_read_b128 v[108:111], v142 offset:6144
	ds_read_b128 v[112:115], v143 offset:0
	ds_read_b128 v[116:119], v143 offset:2048
	ds_read_b128 v[120:123], v143 offset:4096
	ds_read_b128 v[124:127], v143 offset:6144
	s_xor_b32 s18, s18, 0x8000

.Lhwff1b_nextbases:
	s_and_b32 s37, s23, 7
	s_lshr_b32 s38, s23, 3
	s_and_b32 s39, s38, 63
	s_lshr_b32 s44, s38, 6
	s_lshl_b32 s44, s44, 3
	s_add_u32 s44, s44, s37
	s_lshr_b32 s35, s44, 2
	s_lshl_b32 s35, s35, 3
	s_and_b32 s45, s39, 7
	s_add_u32 s35, s35, s45
	s_and_b32 s36, s44, 3
	s_lshl_b32 s36, s36, 3
	s_lshr_b32 s45, s39, 3
	s_add_u32 s36, s36, s45
	s_lshl_b32 s45, s35, 18
	s_add_u32 s45, s45, 0x3cb8000
	s_add_u32 s8, s40, s45
	s_addc_u32 s9, s41, 0
	s_and_b32 s9, s9, 0xffff
	s_lshl_b32 s45, s36, 18
	s_add_u32 s45, s45, 0x2c40000
	s_add_u32 s12, s40, s45
	s_addc_u32 s13, s41, 0
	s_and_b32 s13, s13, 0xffff
	s_branch .Lhwff1b_next

.Lhwff1b_done:
	s_waitcnt lgkmcnt(0)
.LBB0_2443:
	s_waitcnt vmcnt(0)
	s_waitcnt vmcnt(8)
	s_barrier
	s_mov_b64 s[6:7], exec
	v_readlane_b32 s8, v244, 0
	v_readlane_b32 s9, v244, 1
	s_and_b64 s[8:9], s[6:7], s[8:9]
	s_mov_b64 exec, s[8:9]
	s_cbranch_execz .LBB0_2496
	v_cmp_eq_u32_e32 vcc, 0, v192
	s_waitcnt vmcnt(0) expcnt(0) lgkmcnt(0)
	s_and_saveexec_b64 s[8:9], vcc
	s_cbranch_execz .LBB0_2459
	s_add_u32 s10, s40, 0x1f718200
	s_addc_u32 s11, s41, 0
	s_add_u32 s12, s40, 0x1f718400
	s_addc_u32 s13, s41, 0
	s_add_u32 s14, s40, 0x1f718500
	s_addc_u32 s15, s41, 0
	s_add_u32 s16, s40, 0x1f718600
	s_addc_u32 s17, s41, 0
	s_add_u32 s18, s40, 0x1f718700
	s_addc_u32 s19, s41, 0
	s_add_u32 s20, s40, 0x1f718800
	s_addc_u32 s21, s41, 0
	s_add_u32 s22, s40, 0x1f718900
	s_addc_u32 s23, s41, 0
	s_add_u32 s24, s40, 0x1f718a00
	s_addc_u32 s25, s41, 0
	s_add_u32 s26, s40, 0x1f718b00
	s_addc_u32 s27, s41, 0
	s_add_u32 s28, s40, 0x1f718c00
	s_addc_u32 s29, s41, 0
	s_add_u32 s34, s40, 0x1f718d00
	s_addc_u32 s35, s41, 0
	s_add_u32 s36, s40, 0x1f718e00
	s_addc_u32 s37, s41, 0
	s_add_u32 s38, s40, 0x1f718f00
	s_addc_u32 s39, s41, 0
	s_add_u32 s44, s40, 0x1f719000
	s_addc_u32 s45, s41, 0
	s_add_u32 s46, s40, 0x1f719100
	s_addc_u32 s47, s41, 0
	s_add_u32 s48, s40, 0x1f719200
	s_addc_u32 s49, s41, 0
	s_add_u32 s50, s40, 0x1f719300
	s_addc_u32 s51, s41, 0
	s_mov_b32 s58, 1
	v_mov_b32_e32 v16, 0
	s_branch .LBB0_2447

.LBB0_2501:
	s_ashr_i32 s17, s12, 6
	s_and_b32 s6, s12, 7
	s_and_b32 s17, s17, 0x1ffffff8
	s_or_b32 s6, s17, s6
	s_lshl_b32 s6, s6, 3
	s_bfe_u32 s17, s12, 0x30003
	s_or_b32 s6, s6, s17
	s_xor_b64 s[24:25], s[24:25], -1
	s_bfe_u32 s39, s12, 0x30006
	s_sub_i32 s28, 0x13f, s6
	s_ashr_i32 s12, s16, 31
	s_waitcnt lgkmcnt(0)
	s_add_u32 s16, s10, s16
	s_addc_u32 s12, s11, s12
	s_add_u32 s48, s16, 0x8cb8000
	s_addc_u32 s49, s12, 0
	s_ashr_i32 s12, s13, 31
	s_add_u32 s13, s10, s13
	s_addc_u32 s12, s11, s12
	s_add_u32 s50, s13, 0x3440000
	v_mov_b32 v0, 0
	s_addc_u32 s51, s12, 0
	s_ashr_i32 s29, s28, 31
	v_add_u32_e32 v0, v0, v193
	s_lshl_b64 s[12:13], s[28:29], 20
	v_lshrrev_b32_e32 v1, 4, v0
	s_add_u32 s12, s48, s12
	v_xor_b32_e32 v2, v1, v0
	v_lshlrev_b32_e32 v3, 9, v0
	s_addc_u32 s13, s49, s13
	s_lshl_b32 s16, s39, 20
	v_lshlrev_b32_e32 v2, 3, v2
	v_and_b32_e32 v3, 0x7ffff000, v3
	s_add_u32 s16, s50, s16
	v_and_or_b32 v2, v2, 56, v3
	s_addc_u32 s17, s51, 0
	v_lshlrev_b32_e32 v67, 1, v2
	v_lshlrev_b32_e32 v68, 4, v0
	v_readfirstlane_b32 s29, v0
	s_and_b32 s13, s13, 0xffff
	s_and_b32 s17, s17, 0xffff
	v_add_u32_e32 v66, 0x40000, v67
	v_add_u32_e32 v65, 0x80000, v67
	v_add_u32_e32 v64, 0xc0000, v67
	v_lshrrev_b32_e32 v245, 13, v67
	v_and_b32_e32 v246, 0x7f, v67
	v_lshl_or_b32 v245, v245, 7, v246
	v_add_u32_e32 v246, 0x1000, v245
	v_add_u32_e32 v247, 0x2000, v245
	v_add_u32_e32 v248, 0x3000, v245
	s_mov_b64 s[18:19], -1
	s_and_b64 vcc, exec, s[24:25]
	v_add_u32_e32 v69, 0x4000, v68
	v_add_u32_e32 v2, 0x1000, v68
	v_add_u32_e32 v3, 0x2000, v68
	v_add_u32_e32 v4, 0x3000, v68
	s_cbranch_vccz .LBB0_2503
	v_readfirstlane_b32 s18, v68
	s_mov_b32 m0, s18
	v_readfirstlane_b32 s24, v69
	v_add_u32_e32 v70, 0x1000, v68
	buffer_load_dwordx4 v245, s[12:15], 0 offen lds
	s_mov_b32 s18, s14
	s_mov_b32 s19, s15
	s_mov_b32 m0, s24
	v_readfirstlane_b32 s24, v70
	v_add_u32_e32 v5, 0x5000, v68
	buffer_load_dwordx4 v67, s[16:19], 0 offen lds
	s_mov_b32 m0, s24
	v_readfirstlane_b32 s24, v5
	v_add_u32_e32 v71, 0x2000, v68
	buffer_load_dwordx4 v246, s[12:15], 0 offen lds
	s_mov_b32 m0, s24
	v_readfirstlane_b32 s24, v71
	v_add_u32_e32 v5, 0x6000, v68
	buffer_load_dwordx4 v66, s[16:19], 0 offen lds
	s_mov_b32 m0, s24
	v_readfirstlane_b32 s24, v5
	v_add_u32_e32 v72, 0x3000, v68
	buffer_load_dwordx4 v247, s[12:15], 0 offen lds
	s_mov_b32 m0, s24
	v_readfirstlane_b32 s24, v72
	v_add_u32_e32 v5, 0x7000, v68
	buffer_load_dwordx4 v65, s[16:19], 0 offen lds
	s_mov_b32 m0, s24
	v_readfirstlane_b32 s24, v5
	buffer_load_dwordx4 v248, s[12:15], 0 offen lds
	s_mov_b32 m0, s24
	s_nop 0
	buffer_load_dwordx4 v64, s[16:19], 0 offen lds
	s_mov_b64 s[18:19], 0

.LBB0_2505:
	v_bfe_u32 v3, v0, 1, 3
	v_and_b32_e32 v2, 3, v1
	v_bitop3_b32 v1, v1, v3, 3 bitop3:0x6c
	s_lshl_b32 s18, s29, 6
	v_lshlrev_b32_e32 v75, 4, v1
	v_bitop3_b32 v1, v2, v3, 4 bitop3:0x36
	s_and_b32 s52, s18, 0xffffe000
	v_lshlrev_b32_e32 v0, 7, v0
	s_lshl_b32 s18, s29, 7
	v_mov_b32_e32 v40, 0
	s_mov_b64 s[24:25], s[34:35]
	v_lshlrev_b32_e32 v74, 4, v1
	v_and_b32_e32 v73, 0x780, v0
	s_and_b32 s29, s18, 0x2000
	s_movk_i32 s53, 0x80
	s_movk_i32 s98, 0x4000
	s_mov_b32 s54, 0
	s_mov_b32 s18, s14
	s_mov_b32 s19, s15
	v_mov_b32_e32 v41, v40
	v_mov_b32_e32 v42, v40
	v_mov_b32_e32 v43, v40
	v_mov_b32_e32 v0, v40
	v_mov_b32_e32 v1, v40
	v_mov_b32_e32 v2, v40
	v_mov_b32_e32 v3, v40
	v_mov_b32_e32 v4, v40
	v_mov_b32_e32 v5, v40
	v_mov_b32_e32 v6, v40
	v_mov_b32_e32 v7, v40
	v_mov_b32_e32 v8, v40
	v_mov_b32_e32 v9, v40
	v_mov_b32_e32 v10, v40
	v_mov_b32_e32 v11, v40
	v_mov_b32_e32 v12, v40
	v_mov_b32_e32 v13, v40
	s_waitcnt vmcnt(0)
	v_mov_b32_e32 v14, v40
	v_mov_b32_e32 v15, v40
	v_mov_b32_e32 v16, v40
	v_mov_b32_e32 v17, v40
	v_mov_b32_e32 v18, v40
	v_mov_b32_e32 v19, v40
	v_mov_b32_e32 v20, v40
	v_mov_b32_e32 v21, v40
	v_mov_b32_e32 v22, v40
	v_mov_b32_e32 v23, v40
	v_mov_b32_e32 v24, v40
	v_mov_b32_e32 v25, v40
	v_mov_b32_e32 v26, v40
	v_mov_b32_e32 v27, v40
	v_mov_b32_e32 v28, v40
	v_mov_b32_e32 v29, v40
	v_mov_b32_e32 v30, v40
	v_mov_b32_e32 v31, v40
	v_mov_b32_e32 v32, v40
	v_mov_b32_e32 v33, v40
	v_mov_b32_e32 v34, v40
	v_mov_b32_e32 v35, v40
	v_mov_b32_e32 v36, v40
	v_mov_b32_e32 v37, v40
	v_mov_b32_e32 v38, v40
	v_mov_b32_e32 v39, v40
	v_mov_b32_e32 v44, v40
	v_mov_b32_e32 v45, v40
	v_mov_b32_e32 v46, v40
	v_mov_b32_e32 v47, v40
	v_mov_b32_e32 v48, v40
	v_mov_b32_e32 v49, v40
	v_mov_b32_e32 v50, v40
	v_mov_b32_e32 v51, v40
	v_mov_b32_e32 v52, v40
	v_mov_b32_e32 v53, v40
	v_mov_b32_e32 v54, v40
	v_mov_b32_e32 v55, v40
	v_mov_b32_e32 v56, v40
	v_mov_b32_e32 v57, v40
	v_mov_b32_e32 v58, v40
	v_mov_b32_e32 v59, v40
	v_mov_b32_e32 v60, v40
	v_mov_b32_e32 v61, v40
	v_mov_b32_e32 v62, v40
	v_mov_b32_e32 v63, v40
.LBB0_2506:
	s_add_i32 s30, s54, 0x8000
	s_and_b32 s55, s30, 0x8000
	v_add_u32_e32 v76, s55, v68
	s_waitcnt vmcnt(0)
	s_nop 0
	v_readfirstlane_b32 s31, v76
	v_add_u32_e32 v76, 0x4000, v76
	s_mov_b32 m0, s31
	v_readfirstlane_b32 s31, v76
	v_add_u32_e32 v76, s55, v70
	s_barrier
	buffer_load_dwordx4 v245, s[12:15], s98 offen lds
	s_mov_b32 m0, s31
	v_readfirstlane_b32 s31, v76
	v_add_u32_e32 v76, 0x4000, v76
	buffer_load_dwordx4 v67, s[16:19], s53 offen lds
	s_mov_b32 m0, s31
	v_readfirstlane_b32 s31, v76
	v_add_u32_e32 v76, s55, v71
	buffer_load_dwordx4 v246, s[12:15], s98 offen lds
	s_mov_b32 m0, s31
	v_readfirstlane_b32 s31, v76
	v_add_u32_e32 v76, 0x4000, v76
	buffer_load_dwordx4 v66, s[16:19], s53 offen lds
	s_mov_b32 m0, s31
	v_readfirstlane_b32 s31, v76
	v_add_u32_e32 v76, s55, v72
	buffer_load_dwordx4 v247, s[12:15], s98 offen lds
	s_mov_b32 m0, s31
	v_readfirstlane_b32 s31, v76
	v_add_u32_e32 v76, 0x4000, v76
	buffer_load_dwordx4 v65, s[16:19], s53 offen lds
	s_mov_b32 m0, s31
	v_readfirstlane_b32 s31, v76
	buffer_load_dwordx4 v248, s[12:15], s98 offen lds
	s_mov_b32 m0, s31
	s_and_b32 s31, s54, 0x8000
	buffer_load_dwordx4 v64, s[16:19], s53 offen lds
	v_or_b32_e32 v80, s31, v75
	v_add3_u32 v83, v80, s52, v73
	v_add3_u32 v80, v80, s29, v73
	ds_read_b128 v[76:79], v83
	ds_read_b128 v[84:87], v83 offset:2048
	ds_read_b128 v[88:91], v83 offset:4096
	ds_read_b128 v[92:95], v83 offset:6144
	ds_read_b128 v[96:99], v80 offset:16384
	ds_read_b128 v[100:103], v80 offset:18432
	ds_read_b128 v[104:107], v80 offset:20480
	ds_read_b128 v[108:111], v80 offset:22528
	v_or_b32_e32 v80, s31, v74
	v_add3_u32 v83, v80, s52, v73
	v_add3_u32 v80, v80, s29, v73
	ds_read_b128 v[112:115], v83
	ds_read_b128 v[116:119], v83 offset:2048
	ds_read_b128 v[120:123], v83 offset:4096
	ds_read_b128 v[124:127], v83 offset:6144
	ds_read_b128 v[128:131], v80 offset:16384
	ds_read_b128 v[132:135], v80 offset:18432
	ds_read_b128 v[136:139], v80 offset:20480
	ds_read_b128 v[140:143], v80 offset:22528
	s_waitcnt lgkmcnt(11)
	v_mfma_f32_16x16x32_bf16 v[60:63], v[96:99], v[76:79], v[60:63]
	s_waitcnt lgkmcnt(10)
	v_mfma_f32_16x16x32_bf16 v[56:59], v[100:103], v[76:79], v[56:59]
	s_waitcnt lgkmcnt(9)
	v_mfma_f32_16x16x32_bf16 v[52:55], v[104:107], v[76:79], v[52:55]
	s_waitcnt lgkmcnt(8)
	v_mfma_f32_16x16x32_bf16 v[48:51], v[108:111], v[76:79], v[48:51]
	v_mfma_f32_16x16x32_bf16 v[44:47], v[96:99], v[84:87], v[44:47]
	v_mfma_f32_16x16x32_bf16 v[36:39], v[100:103], v[84:87], v[36:39]
	v_mfma_f32_16x16x32_bf16 v[32:35], v[104:107], v[84:87], v[32:35]
	v_mfma_f32_16x16x32_bf16 v[28:31], v[108:111], v[84:87], v[28:31]
	v_mfma_f32_16x16x32_bf16 v[24:27], v[96:99], v[88:91], v[24:27]
	v_mfma_f32_16x16x32_bf16 v[20:23], v[100:103], v[88:91], v[20:23]
	v_mfma_f32_16x16x32_bf16 v[16:19], v[104:107], v[88:91], v[16:19]
	v_mfma_f32_16x16x32_bf16 v[12:15], v[108:111], v[88:91], v[12:15]
	v_mfma_f32_16x16x32_bf16 v[8:11], v[96:99], v[92:95], v[8:11]
	v_mfma_f32_16x16x32_bf16 v[4:7], v[100:103], v[92:95], v[4:7]
	v_mfma_f32_16x16x32_bf16 v[0:3], v[104:107], v[92:95], v[0:3]
	v_mfma_f32_16x16x32_bf16 v[40:43], v[108:111], v[92:95], v[40:43]
	s_waitcnt lgkmcnt(3)
	v_mfma_f32_16x16x32_bf16 v[60:63], v[128:131], v[112:115], v[60:63]
	s_addk_i32 s53, 0x80
	s_addk_i32 s98, 0x4000
	s_cmpk_eq_i32 s53, 0x2000
	s_mov_b32 s54, s30
	s_waitcnt lgkmcnt(2)
	v_mfma_f32_16x16x32_bf16 v[56:59], v[132:135], v[112:115], v[56:59]
	s_waitcnt lgkmcnt(1)
	v_mfma_f32_16x16x32_bf16 v[52:55], v[136:139], v[112:115], v[52:55]
	s_waitcnt lgkmcnt(0)
	v_mfma_f32_16x16x32_bf16 v[48:51], v[140:143], v[112:115], v[48:51]
	v_mfma_f32_16x16x32_bf16 v[44:47], v[128:131], v[116:119], v[44:47]
	v_mfma_f32_16x16x32_bf16 v[36:39], v[132:135], v[116:119], v[36:39]
	v_mfma_f32_16x16x32_bf16 v[32:35], v[136:139], v[116:119], v[32:35]
	v_mfma_f32_16x16x32_bf16 v[28:31], v[140:143], v[116:119], v[28:31]
	v_mfma_f32_16x16x32_bf16 v[24:27], v[128:131], v[120:123], v[24:27]
	v_mfma_f32_16x16x32_bf16 v[20:23], v[132:135], v[120:123], v[20:23]
	v_mfma_f32_16x16x32_bf16 v[16:19], v[136:139], v[120:123], v[16:19]
	v_mfma_f32_16x16x32_bf16 v[12:15], v[140:143], v[120:123], v[12:15]
	v_mfma_f32_16x16x32_bf16 v[8:11], v[128:131], v[124:127], v[8:11]
	v_mfma_f32_16x16x32_bf16 v[4:7], v[132:135], v[124:127], v[4:7]
	v_mfma_f32_16x16x32_bf16 v[0:3], v[136:139], v[124:127], v[0:3]
	v_mfma_f32_16x16x32_bf16 v[40:43], v[140:143], v[124:127], v[40:43]
	s_cbranch_scc0 .LBB0_2506
	s_waitcnt vmcnt(0)
	s_andn2_b64 vcc, exec, s[34:35]
	s_waitcnt vmcnt(0)
	s_barrier
	s_cbranch_vccnz .LBB0_2509
	s_lshl_b64 s[12:13], s[36:37], 1
	s_add_u32 s12, s48, s12
	s_addc_u32 s13, s49, s13
	s_lshl_b32 s16, s38, 1
	s_add_u32 s16, s50, s16
	v_readfirstlane_b32 s30, v68
	s_addc_u32 s17, s51, 0
	s_and_b32 s13, s13, 0xffff
	s_mov_b32 m0, s30
	v_readfirstlane_b32 s30, v69
	v_add_u32_e32 v78, 0x4000, v70
	s_and_b32 s17, s17, 0xffff
	s_mov_b32 s18, s14
	s_mov_b32 s19, s15
	buffer_load_dwordx4 v245, s[12:15], 0 offen lds
	s_mov_b32 m0, s30
	v_readfirstlane_b32 s30, v70
	buffer_load_dwordx4 v67, s[16:19], 0 offen lds
	s_mov_b32 m0, s30
	v_readfirstlane_b32 s30, v78
	v_add_u32_e32 v77, 0x4000, v71
	buffer_load_dwordx4 v246, s[12:15], 0 offen lds
	s_mov_b32 m0, s30
	v_readfirstlane_b32 s30, v71
	buffer_load_dwordx4 v66, s[16:19], 0 offen lds
	s_mov_b32 m0, s30
	v_readfirstlane_b32 s30, v77
	buffer_load_dwordx4 v247, s[12:15], 0 offen lds
	s_mov_b32 m0, s30
	v_readfirstlane_b32 s30, v72
	v_add_u32_e32 v76, 0x4000, v72
	buffer_load_dwordx4 v65, s[16:19], 0 offen lds
	s_mov_b32 m0, s30
	s_nop 0
	buffer_load_dwordx4 v248, s[12:15], 0 offen lds
	v_readfirstlane_b32 s12, v76
	s_mov_b32 m0, s12
	s_nop 0
	buffer_load_dwordx4 v64, s[16:19], 0 offen lds

	.amdhsa_kernel _Z14fwd_megakernel6Params
		.amdhsa_group_segment_fixed_size 65536
		.amdhsa_private_segment_fixed_size 0
		.amdhsa_kernarg_size 504
		.amdhsa_user_sgpr_count 2
		.amdhsa_user_sgpr_dispatch_ptr 0
		.amdhsa_user_sgpr_queue_ptr 0
		.amdhsa_user_sgpr_kernarg_segment_ptr 1
		.amdhsa_user_sgpr_dispatch_id 0
		.amdhsa_user_sgpr_kernarg_preload_length 0
		.amdhsa_user_sgpr_kernarg_preload_offset 0
		.amdhsa_user_sgpr_private_segment_size 0
		.amdhsa_uses_dynamic_stack 0
		.amdhsa_enable_private_segment 0
		.amdhsa_system_sgpr_workgroup_id_x 1
		.amdhsa_system_sgpr_workgroup_id_y 0
		.amdhsa_system_sgpr_workgroup_id_z 0
		.amdhsa_system_sgpr_workgroup_info 0
		.amdhsa_system_vgpr_workitem_id 2
		.amdhsa_next_free_vgpr 249
		.amdhsa_next_free_sgpr 102
		.amdhsa_accum_offset 252
		.amdhsa_reserve_vcc 1
		.amdhsa_float_round_mode_32 0
		.amdhsa_float_round_mode_16_64 0
		.amdhsa_float_denorm_mode_32 3
		.amdhsa_float_denorm_mode_16_64 3
		.amdhsa_dx10_clamp 1
		.amdhsa_ieee_mode 1
		.amdhsa_fp16_overflow 0
		.amdhsa_tg_split 0
		.amdhsa_exception_fp_ieee_invalid_op 0
		.amdhsa_exception_fp_denorm_src 0
		.amdhsa_exception_fp_ieee_div_zero 0
		.amdhsa_exception_fp_ieee_overflow 0
		.amdhsa_exception_fp_ieee_underflow 0
		.amdhsa_exception_fp_ieee_inexact 0
		.amdhsa_exception_int_div_zero 0
	.end_amdhsa_kernel

amdhsa.kernels:
  - .agpr_count:     0
    .args:
      - .offset:         0
        .size:           248
        .value_kind:     by_value
      - .offset:         248
        .size:           4
        .value_kind:     hidden_block_count_x
      - .offset:         252
        .size:           4
        .value_kind:     hidden_block_count_y
      - .offset:         256
        .size:           4
        .value_kind:     hidden_block_count_z
      - .offset:         260
        .size:           2
        .value_kind:     hidden_group_size_x
      - .offset:         262
        .size:           2
        .value_kind:     hidden_group_size_y
      - .offset:         264
        .size:           2
        .value_kind:     hidden_group_size_z
      - .offset:         266
        .size:           2
        .value_kind:     hidden_remainder_x
      - .offset:         268
        .size:           2
        .value_kind:     hidden_remainder_y
      - .offset:         270
        .size:           2
        .value_kind:     hidden_remainder_z
      - .offset:         288
        .size:           8
        .value_kind:     hidden_global_offset_x
      - .offset:         296
        .size:           8
        .value_kind:     hidden_global_offset_y
      - .offset:         304
        .size:           8
        .value_kind:     hidden_global_offset_z
      - .offset:         312
        .size:           2
        .value_kind:     hidden_grid_dims
      - .offset:         336
        .size:           8
        .value_kind:     hidden_multigrid_sync_arg
    .group_segment_fixed_size: 65536
    .kernarg_segment_align: 8
    .kernarg_segment_size: 504
    .language:       OpenCL C
    .language_version:
      - 2
      - 0
    .max_flat_workgroup_size: 256
    .name:           _Z14fwd_megakernel6Params
    .private_segment_fixed_size: 0
    .sgpr_count:     104
    .sgpr_spill_count: 4
    .symbol:         _Z14fwd_megakernel6Params.kd
    .uniform_work_group_size: 1
    .uses_dynamic_stack: false
    .vgpr_count:     249
    .vgpr_spill_count: 0
    .wavefront_size: 64
